# itemwait with MIX1 item split 11:11 (scan workgroups one item fewer in layer 0; the 42 two-rg-item workgroups take 13 chunk-state items)
# speedup vs baseline: 1.0009x; 1.0003x over previous
.LBB0_411:
	s_load_dwordx4 s[28:31], s[0:1], 0x78
	s_load_dwordx2 s[4:5], s[0:1], 0x90
	s_load_dwordx4 s[36:39], s[0:1], 0xa0
	s_mov_b64 s[6:7], -1
	s_and_b64 vcc, exec, s[42:43]
	s_cbranch_vccz .LBB0_413
	v_readlane_b32 s6, v254, 39
	v_readlane_b32 s7, v254, 40
	s_and_b64 s[6:7], s[6:7], exec
	s_movk_i32 s7, 0x2ae
	s_movk_i32 s6, 0x64
	s_cselect_b32 s6, 0x8c, s6
	s_cselect_b32 s7, s7, 0x2d6
	s_add_i32 s8, s7, s6
	s_mul_i32 s9, s94, 13
	s_add_i32 s8, s8, s9
	s_sub_i32 s9, s94, 64
	s_cmp_lt_u32 s9, s6
	s_mul_i32 s13, s9, 5
	s_cselect_b32 s12, 6, 5
	s_add_i32 s7, s13, s7
	s_min_u32 s6, s9, s6
	s_add_i32 s6, s7, s6
	s_add_i32 s7, s6, s12
	s_add_i32 s9, s8, 0xfffff820
	s_addk_i32 s8, 0xf82d
	s_cmpk_lt_u32 s94, 0xd4
	s_cselect_b32 s34, s7, s8
	s_cselect_b32 s51, s6, s9
	s_mov_b64 s[6:7], 0
.LBB0_413:
	s_andn2_b64 vcc, exec, s[6:7]
	s_cbranch_vccnz .LBB0_415
	s_sub_i32 s6, s94, s60
	s_add_i32 s8, s6, 0x42
	s_and_b64 s[6:7], s[10:11], exec
	s_cselect_b32 s6, s94, s8
	s_mul_i32 s7, s6, 6
	s_mul_i32 s9, s6, 11
	s_mul_i32 s11, s6, 11
	s_add_i32 s8, s7, 6
	s_sub_i32 s10, s11, 29
	s_sub_i32 s11, s11, 40
	s_add_i32 s12, s9, 11
	s_cmp_lt_i32 s6, 8
	s_cselect_b32 s8, s8, s10
	s_cselect_b32 s10, s7, s11
	v_readlane_b32 s6, v254, 39
	v_readlane_b32 s7, v254, 40
	s_and_b64 s[6:7], s[6:7], exec
	s_cselect_b32 s34, s8, s12
	s_cselect_b32 s51, s10, s9
